# SB dwordx4+permlane version plus software-pipelined final RMSNorm loop
# baseline (speedup 1.0000x reference)
; __device__ __forceinline__ float rstd_of(float ss, float invn) { return __builtin_amdgcn_rsqf(ss * invn + EPS); }
; __global__ void __launch_bounds__(NTHREADS, 2) fwd_megakernel(Params Pkern) {
;     ...
;     if (PH_ON && PM(11)) {
;         SETUP
;         const float* rsf = RS + (size_t)8 * T; const float* fw = Pp->final_norm;
;         f32x4 w[4];
; #pragma unroll
;         for (int j = 0; j < 4; ++j) w[j] = *((const f32x4*)fw + lane + 64 * j);
;         for (int m = gw; m < T; m += NGW) {
;             const float t = rstd_of(rsf[m], 1.f / 1024.f); f32x4* orow = (f32x4*)(OUT + (size_t)m * DM) + lane;
.LBB0_1436:
	s_cmp_lt_i32 s94, 22
	s_cselect_b64 s[0:1], -1, 0
	s_cmp_gt_i32 s95, 21
	s_cselect_b64 s[2:3], -1, 0
	s_and_b64 s[0:1], s[0:1], s[2:3]
	s_and_b64 vcc, exec, s[0:1]
	s_cbranch_vccz .LBB0_1440
	s_mov_b32 s0, 0x8000
	v_ashrrev_i32_e32 v0, 6, v234
	v_add_u32_e32 v16, s93, v0
	v_cmp_gt_i32_e32 vcc, s0, v16
	s_and_saveexec_b64 s[0:1], vcc
	s_cbranch_execz .LBB0_1440
	s_load_dwordx4 s[0:3], s[90:91], 0xc0
	s_load_dwordx2 s[4:5], s[90:91], 0xd0
	v_lshlrev_b32_e32 v0, 4, v234
	v_and_b32_e32 v22, 0x3f0, v0
	v_ashrrev_i32_e32 v17, 31, v16
	s_waitcnt lgkmcnt(0)
	global_load_dwordx4 v[0:3], v22, s[0:1]
	global_load_dwordx4 v[4:7], v22, s[0:1] offset:1024
	global_load_dwordx4 v[8:11], v22, s[0:1] offset:2048
	global_load_dwordx4 v[12:15], v22, s[0:1] offset:3072
	v_lshlrev_b64 v[20:21], 12, v[16:17]
	v_or_b32_e32 v20, v20, v22
	v_lshl_add_u64 v[18:19], v[16:17], 2, s[4:5]
	s_mov_b64 s[0:1], 0x100000
	v_lshl_add_u64 v[20:21], s[2:3], 0, v[20:21]
	s_mov_b64 s[2:3], 0x800
	v_lshl_add_u64 v[18:19], v[18:19], 0, s[0:1]
	s_lshl_b64 s[0:1], s[26:27], 2
	v_lshl_add_u64 v[20:21], v[20:21], 0, s[2:3]
	s_lshl_b64 s[2:3], s[26:27], 12
	s_mov_b64 s[4:5], 0
	v_mov_b32_e32 v17, 0x358637bd
	s_movk_i32 s6, 0x7fff
	v_readfirstlane_b32 s7, v16
	global_load_dword v38, v[18:19], off
	global_load_dwordx4 v[22:25], v[20:21], off offset:-2048
	global_load_dwordx4 v[26:29], v[20:21], off offset:-1024
	global_load_dwordx4 v[30:33], v[20:21], off
	global_load_dwordx4 v[34:37], v[20:21], off offset:1024
.Lfin_loop:
	s_add_i32 s7, s7, s26
	s_cmp_gt_i32 s7, s6
	s_cbranch_scc1 .Lfin_lastA
	v_lshl_add_u64 v[60:61], v[18:19], 0, s[0:1]
	v_lshl_add_u64 v[62:63], v[20:21], 0, s[2:3]
	global_load_dword v56, v[60:61], off
	global_load_dwordx4 v[40:43], v[62:63], off offset:-2048
	global_load_dwordx4 v[44:47], v[62:63], off offset:-1024
	global_load_dwordx4 v[48:51], v[62:63], off
	global_load_dwordx4 v[52:55], v[62:63], off offset:1024
	s_waitcnt vmcnt(5)
	s_branch .Lfin_compA

; __device__ __forceinline__ float rstd_of(float ss, float invn) { return __builtin_amdgcn_rsqf(ss * invn + EPS); }
; __global__ void __launch_bounds__(NTHREADS, 2) fwd_megakernel(Params Pkern) {
;     ...
;             const float t = rstd_of(rsf[m], 1.f / 1024.f); f32x4* orow = (f32x4*)(OUT + (size_t)m * DM) + lane;
; #pragma unroll
;             for (int j = 0; j < 4; ++j) orow[64 * j] = orow[64 * j] * t * w[j];
.Lfin_compA:
	v_fmamk_f32 v38, v38, 0x3a800000, v17
	v_rsq_f32_e32 v38, v38
	s_nop 0
	v_pk_mul_f32 v[22:23], v[38:39], v[22:23] op_sel_hi:[0,1]
	v_pk_mul_f32 v[24:25], v[38:39], v[24:25] op_sel_hi:[0,1]
	v_pk_mul_f32 v[26:27], v[38:39], v[26:27] op_sel_hi:[0,1]
	v_pk_mul_f32 v[28:29], v[38:39], v[28:29] op_sel_hi:[0,1]
	v_pk_mul_f32 v[30:31], v[38:39], v[30:31] op_sel_hi:[0,1]
	v_pk_mul_f32 v[32:33], v[38:39], v[32:33] op_sel_hi:[0,1]
	v_pk_mul_f32 v[34:35], v[38:39], v[34:35] op_sel_hi:[0,1]
	v_pk_mul_f32 v[36:37], v[38:39], v[36:37] op_sel_hi:[0,1]
	v_pk_mul_f32 v[22:23], v[0:1], v[22:23]
	v_pk_mul_f32 v[24:25], v[2:3], v[24:25]
	v_pk_mul_f32 v[26:27], v[4:5], v[26:27]
	v_pk_mul_f32 v[28:29], v[6:7], v[28:29]
	v_pk_mul_f32 v[30:31], v[8:9], v[30:31]
	v_pk_mul_f32 v[32:33], v[10:11], v[32:33]
	v_pk_mul_f32 v[34:35], v[12:13], v[34:35]
	v_pk_mul_f32 v[36:37], v[14:15], v[36:37]
	global_store_dwordx4 v[20:21], v[22:25], off offset:-2048
	global_store_dwordx4 v[20:21], v[26:29], off offset:-1024
	global_store_dwordx4 v[20:21], v[30:33], off
	global_store_dwordx4 v[20:21], v[34:37], off offset:1024
	s_cmp_gt_i32 s7, s6
	s_cbranch_scc1 .Lfin_done
	s_add_i32 s7, s7, s26
	v_lshl_add_u64 v[18:19], v[60:61], 0, s[0:1]
	v_lshl_add_u64 v[20:21], v[62:63], 0, s[2:3]
	s_cmp_gt_i32 s7, s6
	s_cbranch_scc1 .Lfin_lastB
	global_load_dword v38, v[18:19], off
	global_load_dwordx4 v[22:25], v[20:21], off offset:-2048
	global_load_dwordx4 v[26:29], v[20:21], off offset:-1024
	global_load_dwordx4 v[30:33], v[20:21], off
	global_load_dwordx4 v[34:37], v[20:21], off offset:1024
	s_waitcnt vmcnt(5)
	s_branch .Lfin_compB

; __device__ __forceinline__ float rstd_of(float ss, float invn) { return __builtin_amdgcn_rsqf(ss * invn + EPS); }
; __global__ void __launch_bounds__(NTHREADS, 2) fwd_megakernel(Params Pkern) {
;     ...
;             const float t = rstd_of(rsf[m], 1.f / 1024.f); f32x4* orow = (f32x4*)(OUT + (size_t)m * DM) + lane;
; #pragma unroll
;             for (int j = 0; j < 4; ++j) orow[64 * j] = orow[64 * j] * t * w[j];
;         }
.Lfin_compB:
	v_fmamk_f32 v56, v56, 0x3a800000, v17
	v_rsq_f32_e32 v56, v56
	s_nop 0
	v_pk_mul_f32 v[40:41], v[56:57], v[40:41] op_sel_hi:[0,1]
	v_pk_mul_f32 v[42:43], v[56:57], v[42:43] op_sel_hi:[0,1]
	v_pk_mul_f32 v[44:45], v[56:57], v[44:45] op_sel_hi:[0,1]
	v_pk_mul_f32 v[46:47], v[56:57], v[46:47] op_sel_hi:[0,1]
	v_pk_mul_f32 v[48:49], v[56:57], v[48:49] op_sel_hi:[0,1]
	v_pk_mul_f32 v[50:51], v[56:57], v[50:51] op_sel_hi:[0,1]
	v_pk_mul_f32 v[52:53], v[56:57], v[52:53] op_sel_hi:[0,1]
	v_pk_mul_f32 v[54:55], v[56:57], v[54:55] op_sel_hi:[0,1]
	v_pk_mul_f32 v[40:41], v[0:1], v[40:41]
	v_pk_mul_f32 v[42:43], v[2:3], v[42:43]
	v_pk_mul_f32 v[44:45], v[4:5], v[44:45]
	v_pk_mul_f32 v[46:47], v[6:7], v[46:47]
	v_pk_mul_f32 v[48:49], v[8:9], v[48:49]
	v_pk_mul_f32 v[50:51], v[10:11], v[50:51]
	v_pk_mul_f32 v[52:53], v[12:13], v[52:53]
	v_pk_mul_f32 v[54:55], v[14:15], v[54:55]
	global_store_dwordx4 v[62:63], v[40:43], off offset:-2048
	global_store_dwordx4 v[62:63], v[44:47], off offset:-1024
	global_store_dwordx4 v[62:63], v[48:51], off
	global_store_dwordx4 v[62:63], v[52:55], off offset:1024
	s_cmp_gt_i32 s7, s6
	s_cbranch_scc0 .Lfin_loop
.Lfin_done:
.LBB0_1440:
	s_endpgm
